# P8/P9 order mixing keyed on workgroup id bit 0 (XCD parity) instead of bit 3
# baseline (speedup 1.0000x reference)
.LBB0_1548:
	s_bitcmp1_b32 s33, 0
	s_cbranch_scc0 .Lp8_enter
	s_cmp_lg_u32 s101, 0
	s_cbranch_scc1 .Lp8_enter
	s_mov_b32 s101, 1
	s_branch .LBB0_1602
	s_nop 0
	s_nop 0
	s_nop 0
	s_nop 0
	s_nop 0
	s_nop 0
	s_nop 0
	s_nop 0
	s_nop 0
	s_nop 0
